# scan stage D epilogue (mask+store) hand-written in all 3 loops; stage C hand-written in segment-transition loop too
# speedup vs baseline: 1.0939x; 1.0227x over previous
.LBB0_933:
	v_lshlrev_b32_e32 v32, 2, v114
	v_add3_u32 v32, s10, v32, v42
	v_and_b32_e32 v116, 7, v113
	ds_write_b32 v32, v43 offset:7020
	s_waitcnt lgkmcnt(0)
	s_barrier
	s_waitcnt vmcnt(0)
	v_lshrrev_b32_e32 v41, 3, v113
	v_lshlrev_b32_e32 v168, 5, v116
	v_mul_u32_u24_e32 v136, 0x104, v41
	v_cmp_lt_u32_e32 vcc, 0, v41
	v_add_u32_e32 v169, v136, v168
	v_mov_b32_e32 v137, 0x104
	v_add_u32_e32 v170, 0x2080, v169
	ds_read_b128 v[178:181], v168 offset:61120
	ds_read_b128 v[182:185], v168 offset:61136
	ds_read2_b32 v[194:195], v170 offset0:0 offset1:1
	ds_read2_b32 v[196:197], v170 offset0:2 offset1:3
	ds_read2_b32 v[198:199], v170 offset0:4 offset1:5
	ds_read2_b32 v[200:201], v170 offset0:6 offset1:7
	ds_read_b128 v[208:211], v168 offset:61376
	ds_read_b128 v[212:215], v168 offset:61392
	ds_read2_b32 v[224:225], v169 offset0:0 offset1:1
	ds_read2_b32 v[226:227], v169 offset0:2 offset1:3
	ds_read2_b32 v[228:229], v169 offset0:4 offset1:5
	ds_read2_b32 v[230:231], v169 offset0:6 offset1:7
	v_mov_b32_e32 v232, 0x3fb8aa3b
	v_mov_b32_e32 v233, 0x3fb8aa3b
	v_cndmask_b32_e32 v137, 0, v137, vcc
	v_cndmask_b32_e32 v171, 0, v232, vcc
	v_mov_b32_e32 v234, 1.0
	v_mov_b32_e32 v235, 1.0
	v_sub_u32_e32 v172, v169, v137
	v_add_u32_e32 v173, 0x1f7c, v168
	v_mul_u32_u24_e32 v174, 0x280, v116
	v_lshrrev_b32_e32 v136, 3, v41
	v_and_b32_e32 v138, 4, v116
	v_xor_b32_e32 v136, v136, v116
	v_lshl_add_u32 v174, v138, 4, v174
	v_and_b32_e32 v136, 3, v136
	v_and_b32_e32 v138, 7, v41
	v_lshl_add_u32 v174, v136, 4, v174
	v_mul_u32_u24_e32 v175, 0x90, v41
	v_lshl_add_u32 v174, v138, 1, v174
	v_lshl_add_u32 v175, v116, 4, v175
	v_lshlrev_b32_e32 v186, 16, v84
	v_and_b32_e32 v187, 0xffff0000, v84
	v_lshlrev_b32_e32 v188, 16, v85
	v_and_b32_e32 v189, 0xffff0000, v85
	v_lshlrev_b32_e32 v190, 16, v86
	v_and_b32_e32 v191, 0xffff0000, v86
	v_lshlrev_b32_e32 v192, 16, v87
	v_and_b32_e32 v193, 0xffff0000, v87
	s_waitcnt lgkmcnt(0)
	ds_read2_b32 v[120:121], v173 offset0:0 offset1:1
	ds_read2_b32 v[122:123], v173 offset0:2 offset1:3
	ds_read2_b32 v[124:125], v173 offset0:4 offset1:5
	ds_read2_b32 v[126:127], v173 offset0:6 offset1:7
	ds_read2_b32 v[128:129], v172 offset0:0 offset1:1
	ds_read2_b32 v[130:131], v172 offset0:2 offset1:3
	ds_read2_b32 v[132:133], v172 offset0:4 offset1:5
	ds_read2_b32 v[134:135], v172 offset0:6 offset1:7
	v_pk_mul_f32 v[178:179], v[178:179], v[186:187]
	v_pk_mul_f32 v[180:181], v[180:181], v[188:189]
	v_pk_mul_f32 v[182:183], v[182:183], v[190:191]
	v_pk_mul_f32 v[184:185], v[184:185], v[192:193]
	v_pk_mul_f32 v[166:167], v[178:179], v[178:179]
	v_pk_fma_f32 v[166:167], v[180:181], v[180:181], v[166:167]
	v_pk_fma_f32 v[166:167], v[182:183], v[182:183], v[166:167]
	v_pk_fma_f32 v[166:167], v[184:185], v[184:185], v[166:167]
	v_pk_add_f32 v[216:217], v[194:195], v[234:235] neg_lo:[0,1] neg_hi:[0,1]
	v_pk_add_f32 v[218:219], v[196:197], v[234:235] neg_lo:[0,1] neg_hi:[0,1]
	v_pk_add_f32 v[220:221], v[198:199], v[234:235] neg_lo:[0,1] neg_hi:[0,1]
	v_pk_add_f32 v[222:223], v[200:201], v[234:235] neg_lo:[0,1] neg_hi:[0,1]
	v_add_f32_e32 v166, v166, v167
	v_pk_fma_f32 v[208:209], v[216:217], v[208:209], v[234:235]
	v_pk_fma_f32 v[210:211], v[218:219], v[210:211], v[234:235]
	v_add_f32_dpp v166, v166, v166 quad_perm:[1,0,3,2] row_mask:0xf bank_mask:0xf bound_ctrl:1
	v_pk_fma_f32 v[212:213], v[220:221], v[212:213], v[234:235]
	v_pk_fma_f32 v[214:215], v[222:223], v[214:215], v[234:235]
	v_add_f32_dpp v166, v166, v166 quad_perm:[2,3,0,1] row_mask:0xf bank_mask:0xf bound_ctrl:1
	v_pk_mul_f32 v[186:187], v[186:187], v[208:209]
	v_pk_mul_f32 v[188:189], v[188:189], v[210:211]
	v_mov_b32_dpp v167, v166 row_half_mirror row_mask:0xf bank_mask:0xf bound_ctrl:1
	v_pk_mul_f32 v[190:191], v[190:191], v[212:213]
	v_pk_mul_f32 v[192:193], v[192:193], v[214:215]
	v_add_f32_e32 v166, v166, v167
	v_add_f32_e32 v166, 0x2b8cbccc, v166
	v_rsq_f32_e32 v166, v166
	s_waitcnt lgkmcnt(0)
	v_pk_mul_f32 v[178:179], v[178:179], v[166:167] op_sel_hi:[1,0]
	v_pk_mul_f32 v[180:181], v[180:181], v[166:167] op_sel_hi:[1,0]
	v_pk_mul_f32 v[182:183], v[182:183], v[166:167] op_sel_hi:[1,0]
	v_pk_mul_f32 v[184:185], v[184:185], v[166:167] op_sel_hi:[1,0]
	v_cmp_eq_u32_e32 vcc, 31, v41
	v_pk_mul_f32 v[216:217], v[178:179], v[194:195]
	v_pk_mul_f32 v[218:219], v[180:181], v[196:197]
	v_pk_mul_f32 v[220:221], v[182:183], v[198:199]
	v_pk_mul_f32 v[222:223], v[184:185], v[200:201]
	s_and_saveexec_b64 s[38:39], vcc
	s_cbranch_execz .Lc_nogc_a
	v_pk_mul_f32 v[194:195], v[120:121], v[232:233]
	v_pk_mul_f32 v[196:197], v[122:123], v[232:233]
	v_pk_mul_f32 v[198:199], v[124:125], v[232:233]
	v_pk_mul_f32 v[200:201], v[126:127], v[232:233]
	v_exp_f32_e64 v194, v194
	v_exp_f32_e64 v195, v195
	v_exp_f32_e64 v196, v196
	v_exp_f32_e64 v197, v197
	v_exp_f32_e64 v198, v198
	v_exp_f32_e64 v199, v199
	v_exp_f32_e64 v200, v200
	v_exp_f32_e64 v201, v201
	ds_write_b128 v168, v[194:197] offset:60864
	ds_write_b128 v168, v[198:201] offset:60880
.Lc_nogc_a:
	s_or_b64 exec, exec, s[38:39]
	v_pk_add_f32 v[120:121], v[120:121], v[224:225] neg_lo:[0,1] neg_hi:[0,1]
	v_pk_add_f32 v[122:123], v[122:123], v[226:227] neg_lo:[0,1] neg_hi:[0,1]
	v_pk_add_f32 v[124:125], v[124:125], v[228:229] neg_lo:[0,1] neg_hi:[0,1]
	v_pk_add_f32 v[126:127], v[126:127], v[230:231] neg_lo:[0,1] neg_hi:[0,1]
	v_pk_mul_f32 v[120:121], v[120:121], v[232:233]
	v_pk_mul_f32 v[122:123], v[122:123], v[232:233]
	v_pk_mul_f32 v[124:125], v[124:125], v[232:233]
	v_pk_mul_f32 v[126:127], v[126:127], v[232:233]
	v_pk_mul_f32 v[224:225], v[224:225], v[232:233]
	v_pk_mul_f32 v[226:227], v[226:227], v[232:233]
	v_pk_mul_f32 v[228:229], v[228:229], v[232:233]
	v_pk_mul_f32 v[230:231], v[230:231], v[232:233]
	v_exp_f32_e64 v120, v120
	v_exp_f32_e64 v121, v121
	v_exp_f32_e64 v122, v122
	v_exp_f32_e64 v123, v123
	v_exp_f32_e64 v124, v124
	v_exp_f32_e64 v125, v125
	v_exp_f32_e64 v126, v126
	v_exp_f32_e64 v127, v127
	v_mul_f32_e32 v128, v171, v128
	v_mul_f32_e32 v129, v171, v129
	v_mul_f32_e32 v130, v171, v130
	v_mul_f32_e32 v131, v171, v131
	v_mul_f32_e32 v132, v171, v132
	v_mul_f32_e32 v133, v171, v133
	v_mul_f32_e32 v134, v171, v134
	v_mul_f32_e32 v135, v171, v135
	v_pk_mul_f32 v[194:195], v[216:217], v[120:121]
	v_pk_mul_f32 v[196:197], v[218:219], v[122:123]
	v_pk_mul_f32 v[198:199], v[220:221], v[124:125]
	v_pk_mul_f32 v[200:201], v[222:223], v[126:127]
	v_pk_mul_f32 v[120:121], v[186:187], v[120:121]
	v_pk_mul_f32 v[122:123], v[188:189], v[122:123]
	v_pk_mul_f32 v[124:125], v[190:191], v[124:125]
	v_pk_mul_f32 v[126:127], v[192:193], v[126:127]
	v_cvt_pk_bf16_f32 v194, v194, v195
	v_cvt_pk_bf16_f32 v195, v196, v197
	v_cvt_pk_bf16_f32 v196, v198, v199
	v_cvt_pk_bf16_f32 v197, v200, v201
	v_cvt_pk_bf16_f32 v198, v120, v121
	v_cvt_pk_bf16_f32 v199, v122, v123
	v_cvt_pk_bf16_f32 v200, v124, v125
	v_cvt_pk_bf16_f32 v201, v126, v127
	ds_write_b16 v174, v194 offset:35072
	ds_write_b16_d16_hi v174, v194 offset:35152
	ds_write_b16 v174, v195 offset:35232
	ds_write_b16_d16_hi v174, v195 offset:35312
	ds_write_b16 v174, v196 offset:35392
	ds_write_b16_d16_hi v174, v196 offset:35472
	ds_write_b16 v174, v197 offset:35552
	ds_write_b16_d16_hi v174, v197 offset:35632
	v_exp_f32_e64 v128, v128
	v_exp_f32_e64 v129, v129
	v_exp_f32_e64 v130, v130
	v_exp_f32_e64 v131, v131
	v_exp_f32_e64 v132, v132
	v_exp_f32_e64 v133, v133
	v_exp_f32_e64 v134, v134
	v_exp_f32_e64 v135, v135
	ds_write_b16 v174, v198 offset:40256
	ds_write_b16_d16_hi v174, v198 offset:40336
	ds_write_b16 v174, v199 offset:40416
	s_waitcnt lgkmcnt(5)
	ds_write_b16_d16_hi v174, v199 offset:40496
	ds_write_b16 v174, v200 offset:40576
	ds_write_b16_d16_hi v174, v200 offset:40656
	ds_write_b16 v174, v201 offset:40736
	ds_write_b16_d16_hi v174, v201 offset:40816
	ds_write_b16 v174, v80 offset:45440
	ds_write_b16_d16_hi v174, v80 offset:45520
	ds_write_b16 v174, v81 offset:45600
	s_waitcnt lgkmcnt(5)
	ds_write_b16_d16_hi v174, v81 offset:45680
	ds_write_b16 v174, v82 offset:45760
	ds_write_b16_d16_hi v174, v82 offset:45840
	ds_write_b16 v174, v83 offset:45920
	ds_write_b16_d16_hi v174, v83 offset:46000
	v_pk_mul_f32 v[128:129], v[178:179], v[128:129] neg_lo:[1,0] neg_hi:[1,0]
	v_pk_mul_f32 v[130:131], v[180:181], v[130:131] neg_lo:[1,0] neg_hi:[1,0]
	v_pk_mul_f32 v[132:133], v[182:183], v[132:133] neg_lo:[1,0] neg_hi:[1,0]
	v_pk_mul_f32 v[134:135], v[184:185], v[134:135] neg_lo:[1,0] neg_hi:[1,0]
	v_exp_f32_e64 v120, -v224
	v_exp_f32_e64 v121, -v225
	v_exp_f32_e64 v122, -v226
	v_exp_f32_e64 v123, -v227
	v_exp_f32_e64 v124, -v228
	v_exp_f32_e64 v125, -v229
	v_exp_f32_e64 v126, -v230
	v_exp_f32_e64 v127, -v231
	v_cvt_pk_bf16_f32 v128, v128, v129
	v_cvt_pk_bf16_f32 v129, v130, v131
	v_cvt_pk_bf16_f32 v130, v132, v133
	v_cvt_pk_bf16_f32 v131, v134, v135
	s_waitcnt lgkmcnt(8)
	ds_write_b128 v175, v[128:131] offset:16640
	v_pk_mul_f32 v[216:217], v[216:217], v[120:121]
	v_pk_mul_f32 v[218:219], v[218:219], v[122:123]
	v_pk_mul_f32 v[220:221], v[220:221], v[124:125]
	v_pk_mul_f32 v[222:223], v[222:223], v[126:127]
	v_pk_mul_f32 v[186:187], v[186:187], v[120:121]
	v_pk_mul_f32 v[188:189], v[188:189], v[122:123]
	v_pk_mul_f32 v[190:191], v[190:191], v[124:125]
	v_pk_mul_f32 v[192:193], v[192:193], v[126:127]
	v_cvt_pk_bf16_f32 v216, v216, v217
	v_cvt_pk_bf16_f32 v217, v218, v219
	v_cvt_pk_bf16_f32 v218, v220, v221
	v_cvt_pk_bf16_f32 v219, v222, v223
	v_cvt_pk_bf16_f32 v186, v186, v187
	v_cvt_pk_bf16_f32 v187, v188, v189
	v_cvt_pk_bf16_f32 v188, v190, v191
	v_cvt_pk_bf16_f32 v189, v192, v193
	s_waitcnt lgkmcnt(8)
	ds_write_b128 v175, v[216:219] offset:25856
	ds_write_b128 v175, v[186:189] offset:30464
	v_lshlrev_b32_e32 v47, 3, v116
	s_andn2_b64 vcc, exec, s[36:37]
	s_cbranch_vccnz .LBB0_967
	v_sub_u32_e32 v32, 31, v41
	v_cndmask_b32_e64 v32, v32, v41, s[6:7]
	v_add_u32_e32 v32, s54, v32
	v_ashrrev_i32_e32 v33, 31, v32
	v_or_b32_e32 v36, s35, v47
	v_lshlrev_b64 v[32:33], 11, v[32:33]
	v_lshl_add_u64 v[34:35], s[16:17], 0, v[32:33]
	v_lshlrev_b32_e32 v36, 1, v36
	v_mov_b32_e32 v37, v97
	v_lshl_add_u64 v[34:35], v[34:35], 0, v[36:37]
	v_lshl_add_u64 v[32:33], s[26:27], 0, v[32:33]
	v_lshl_add_u64 v[32:33], v[32:33], 0, v[36:37]
	global_load_dwordx4 v[84:87], v[34:35], off
	global_load_dwordx4 v[80:83], v[32:33], off
.LBB0_967:
	s_waitcnt lgkmcnt(0)
	s_barrier
	s_andn2_b64 vcc, exec, s[20:21]
	v_lshlrev_b32_e32 v98, 2, v115
	s_cbranch_vccnz .LBB0_1032
	v_mul_u32_u24_e32 v32, 0x48, v112
	v_lshlrev_b32_e32 v89, 1, v32
	v_add_u32_e32 v88, v89, v96
	ds_read_b128 v[32:35], v88 offset:16640
	v_add3_u32 v94, s42, v89, v96
	ds_read_b128 v[36:39], v94
	ds_read_b128 v[90:93], v88 offset:16672
	ds_read_b128 v[116:119], v94 offset:32
	v_cmp_lt_u32_e64 s[10:11], v112, v98
	s_mov_b64 s[36:37], -1
	s_and_b64 vcc, exec, s[30:31]
	s_waitcnt lgkmcnt(2)
	v_mfma_f32_32x32x16_bf16 v[32:47], v[32:35], v[36:39], 0
	s_waitcnt lgkmcnt(0)
	v_mfma_f32_32x32x16_bf16 v[32:47], v[90:93], v[116:119], v[32:47]
	ds_read_b128 v[90:93], v88 offset:16704
	ds_read_b128 v[116:119], v94 offset:64
	ds_read_b128 v[120:123], v88 offset:16736
	ds_read_b128 v[124:127], v94 offset:96
	v_lshl_add_u32 v88, v112, 1, s43
	s_waitcnt lgkmcnt(2)
	v_mfma_f32_32x32x16_bf16 v[32:47], v[90:93], v[116:119], v[32:47]
	s_waitcnt lgkmcnt(0)
	v_mfma_f32_32x32x16_bf16 v[32:47], v[120:123], v[124:127], v[32:47]
	v_or_b32_e32 v213, 1, v98
	v_or_b32_e32 v214, 2, v98
	v_or_b32_e32 v215, 3, v98
	v_or_b32_e32 v216, 8, v98
	v_or_b32_e32 v217, 9, v98
	v_or_b32_e32 v218, 10, v98
	v_or_b32_e32 v219, 11, v98
	v_or_b32_e32 v220, 16, v98
	v_or_b32_e32 v221, 17, v98
	v_or_b32_e32 v222, 18, v98
	v_or_b32_e32 v223, 19, v98
	v_or_b32_e32 v224, 24, v98
	v_or_b32_e32 v225, 25, v98
	v_or_b32_e32 v226, 26, v98
	v_or_b32_e32 v227, 27, v98
	s_cmp_eq_u64 s[30:31], 0
	s_cbranch_scc1 .Ld_w0_a
	v_mul_u32_u24_e32 v89, 0x50, v98
	v_add_u32_e32 v89, v89, v88
	v_cmp_lt_u32_e32 vcc, v112, v98
	v_cmp_lt_u32_e64 s[10:11], v112, v213
	v_cmp_lt_u32_e64 s[36:37], v112, v214
	v_cndmask_b32_e64 v32, 0, v32, vcc
	v_cmp_lt_u32_e32 vcc, v112, v215
	v_cndmask_b32_e64 v33, 0, v33, s[10:11]
	v_cmp_lt_u32_e64 s[10:11], v112, v216
	v_cvt_pk_bf16_f32 v90, v32, v33
	ds_write_b16 v89, v90 offset:0
	ds_write_b16_d16_hi v89, v90 offset:80
	v_cndmask_b32_e64 v34, 0, v34, s[36:37]
	v_cmp_lt_u32_e64 s[36:37], v112, v217
	v_cndmask_b32_e64 v35, 0, v35, vcc
	v_cmp_lt_u32_e32 vcc, v112, v218
	v_cvt_pk_bf16_f32 v90, v34, v35
	ds_write_b16 v89, v90 offset:160
	ds_write_b16_d16_hi v89, v90 offset:240
	v_cndmask_b32_e64 v36, 0, v36, s[10:11]
	v_cmp_lt_u32_e64 s[10:11], v112, v219
	v_cndmask_b32_e64 v37, 0, v37, s[36:37]
	v_cmp_lt_u32_e64 s[36:37], v112, v220
	v_cvt_pk_bf16_f32 v90, v36, v37
	ds_write_b16 v89, v90 offset:640
	ds_write_b16_d16_hi v89, v90 offset:720
	v_cndmask_b32_e64 v38, 0, v38, vcc
	v_cmp_lt_u32_e32 vcc, v112, v221
	v_cndmask_b32_e64 v39, 0, v39, s[10:11]
	v_cmp_lt_u32_e64 s[10:11], v112, v222
	v_cvt_pk_bf16_f32 v90, v38, v39
	ds_write_b16 v89, v90 offset:800
	ds_write_b16_d16_hi v89, v90 offset:880
	v_cndmask_b32_e64 v40, 0, v40, s[36:37]
	v_cmp_lt_u32_e64 s[36:37], v112, v223
	v_cndmask_b32_e64 v41, 0, v41, vcc
	v_cmp_lt_u32_e32 vcc, v112, v224
	v_cvt_pk_bf16_f32 v90, v40, v41
	ds_write_b16 v89, v90 offset:1280
	ds_write_b16_d16_hi v89, v90 offset:1360
	v_cndmask_b32_e64 v42, 0, v42, s[10:11]
	v_cmp_lt_u32_e64 s[10:11], v112, v225
	v_cndmask_b32_e64 v43, 0, v43, s[36:37]
	v_cmp_lt_u32_e64 s[36:37], v112, v226
	v_cvt_pk_bf16_f32 v90, v42, v43
	ds_write_b16 v89, v90 offset:1440
	ds_write_b16_d16_hi v89, v90 offset:1520
	v_cndmask_b32_e64 v44, 0, v44, vcc
	v_cmp_lt_u32_e32 vcc, v112, v227
	v_cndmask_b32_e64 v45, 0, v45, s[10:11]
	v_cvt_pk_bf16_f32 v90, v44, v45
	ds_write_b16 v89, v90 offset:1920
	ds_write_b16_d16_hi v89, v90 offset:2000
	v_cndmask_b32_e64 v46, 0, v46, s[36:37]
	v_cndmask_b32_e64 v47, 0, v47, vcc
	v_cvt_pk_bf16_f32 v90, v46, v47
	ds_write_b16 v89, v90 offset:2080
	ds_write_b16_d16_hi v89, v90 offset:2160
	s_branch .Ld_done_a
.Ld_w0_a:
	v_mul_u32_u24_e32 v89, 0x84, v112
	v_lshl_add_u32 v89, v98, 2, v89
	v_add_u32_e32 v89, 0x2080, v89
	v_cmp_lt_u32_e32 vcc, v112, v98
	v_cmp_lt_u32_e64 s[10:11], v112, v213
	v_cmp_lt_u32_e64 s[36:37], v112, v214
	v_cndmask_b32_e64 v32, 0, v32, vcc
	v_cmp_lt_u32_e32 vcc, v112, v215
	v_cndmask_b32_e64 v33, 0, v33, s[10:11]
	v_cmp_lt_u32_e64 s[10:11], v112, v216
	ds_write2_b32 v89, v32, v33 offset0:0 offset1:1
	v_cndmask_b32_e64 v34, 0, v34, s[36:37]
	v_cmp_lt_u32_e64 s[36:37], v112, v217
	v_cndmask_b32_e64 v35, 0, v35, vcc
	v_cmp_lt_u32_e32 vcc, v112, v218
	ds_write2_b32 v89, v34, v35 offset0:2 offset1:3
	v_cndmask_b32_e64 v36, 0, v36, s[10:11]
	v_cmp_lt_u32_e64 s[10:11], v112, v219
	v_cndmask_b32_e64 v37, 0, v37, s[36:37]
	v_cmp_lt_u32_e64 s[36:37], v112, v220
	ds_write2_b32 v89, v36, v37 offset0:8 offset1:9
	v_cndmask_b32_e64 v38, 0, v38, vcc
	v_cmp_lt_u32_e32 vcc, v112, v221
	v_cndmask_b32_e64 v39, 0, v39, s[10:11]
	v_cmp_lt_u32_e64 s[10:11], v112, v222
	ds_write2_b32 v89, v38, v39 offset0:10 offset1:11
	v_cndmask_b32_e64 v40, 0, v40, s[36:37]
	v_cmp_lt_u32_e64 s[36:37], v112, v223
	v_cndmask_b32_e64 v41, 0, v41, vcc
	v_cmp_lt_u32_e32 vcc, v112, v224
	ds_write2_b32 v89, v40, v41 offset0:16 offset1:17
	v_cndmask_b32_e64 v42, 0, v42, s[10:11]
	v_cmp_lt_u32_e64 s[10:11], v112, v225
	v_cndmask_b32_e64 v43, 0, v43, s[36:37]
	v_cmp_lt_u32_e64 s[36:37], v112, v226
	ds_write2_b32 v89, v42, v43 offset0:18 offset1:19
	v_cndmask_b32_e64 v44, 0, v44, vcc
	v_cmp_lt_u32_e32 vcc, v112, v227
	v_cndmask_b32_e64 v45, 0, v45, s[10:11]
	ds_write2_b32 v89, v44, v45 offset0:24 offset1:25
	v_cndmask_b32_e64 v46, 0, v46, s[36:37]
	v_cndmask_b32_e64 v47, 0, v47, vcc
	ds_write2_b32 v89, v46, v47 offset0:26 offset1:27
.Ld_done_a:
.LBB0_1032:
	v_cmp_gt_i32_e32 vcc, 32, v113
	v_and_b32_e32 v32, 15, v113
	s_and_saveexec_b64 s[36:37], vcc
	s_cbranch_execz .LBB0_1034
	v_lshrrev_b32_e32 v99, 4, v113
	v_mul_u32_u24_e32 v33, 0x880, v99
	v_add_u32_e32 v33, 0x2080, v33
	v_add_u32_e32 v96, 0x420, v33
	v_cmp_eq_u32_e32 vcc, 0, v32
	v_cmp_eq_u32_e64 s[10:11], 1, v32
	ds_read_b32 v116, v33 offset:4
	v_cndmask_b32_e64 v34, 0, 1.0, vcc
	ds_read2_b32 v[118:119], v33 offset0:2 offset1:3
	v_cmp_eq_u32_e32 vcc, 2, v32
	v_cndmask_b32_e64 v35, 0, 1.0, s[10:11]
	ds_read2_b32 v[120:121], v33 offset0:4 offset1:5
	v_cmp_eq_u32_e64 s[10:11], 3, v32
	v_cndmask_b32_e64 v36, 0, 1.0, vcc
	ds_read2_b32 v[122:123], v33 offset0:6 offset1:7
	v_cmp_eq_u32_e32 vcc, 4, v32
	v_cndmask_b32_e64 v37, 0, 1.0, s[10:11]
	ds_read2_b32 v[124:125], v33 offset0:8 offset1:9
	v_cmp_eq_u32_e64 s[10:11], 5, v32
	v_cndmask_b32_e64 v38, 0, 1.0, vcc
	ds_read2_b32 v[126:127], v33 offset0:10 offset1:11
	v_cmp_eq_u32_e32 vcc, 6, v32
	v_cndmask_b32_e64 v39, 0, 1.0, s[10:11]
	ds_read2_b32 v[88:89], v33 offset0:12 offset1:13
	v_cmp_eq_u32_e64 s[10:11], 7, v32
	v_cndmask_b32_e64 v40, 0, 1.0, vcc
	ds_read2_b32 v[90:91], v33 offset0:14 offset1:15
	v_cmp_eq_u32_e32 vcc, 8, v32
	v_cndmask_b32_e64 v41, 0, 1.0, s[10:11]
	ds_read2_b32 v[92:93], v33 offset0:35 offset1:36
	v_cmp_eq_u32_e64 s[10:11], 9, v32
	v_cndmask_b32_e64 v42, 0, 1.0, vcc
	ds_read2_b32 v[94:95], v33 offset0:37 offset1:38
	v_cmp_eq_u32_e32 vcc, 10, v32
	v_cndmask_b32_e64 v43, 0, 1.0, s[10:11]
	v_cmp_eq_u32_e64 s[10:11], 11, v32
	v_cndmask_b32_e64 v44, 0, 1.0, vcc
	v_cmp_eq_u32_e32 vcc, 12, v32
	v_cndmask_b32_e64 v45, 0, 1.0, s[10:11]
	v_cmp_eq_u32_e64 s[10:11], 13, v32
	v_cndmask_b32_e64 v46, 0, 1.0, vcc
	v_cmp_eq_u32_e32 vcc, 14, v32
	v_cndmask_b32_e64 v47, 0, 1.0, s[10:11]
	v_cmp_eq_u32_e64 s[10:11], 15, v32
	v_cndmask_b32_e64 v100, 0, 1.0, vcc
	s_nop 0
	v_cndmask_b32_e64 v101, 0, 1.0, s[10:11]
	s_waitcnt lgkmcnt(6)
	v_fmac_f32_e32 v35, v34, v116
	v_pk_fma_f32 v[36:37], v[34:35], v[118:119], v[36:37] op_sel:[0,0,0] op_sel_hi:[0,1,1]
	v_pk_fma_f32 v[38:39], v[34:35], v[120:121], v[38:39] op_sel:[0,0,0] op_sel_hi:[0,1,1]
	v_pk_fma_f32 v[40:41], v[34:35], v[122:123], v[40:41] op_sel:[0,0,0] op_sel_hi:[0,1,1]
	ds_read2_b32 v[116:117], v33 offset0:39 offset1:40
	ds_read2_b32 v[118:119], v33 offset0:41 offset1:42
	ds_read2_b32 v[120:121], v33 offset0:43 offset1:44
	ds_read2_b32 v[122:123], v33 offset0:45 offset1:46
	s_waitcnt lgkmcnt(6)
	v_pk_fma_f32 v[42:43], v[34:35], v[124:125], v[42:43] op_sel:[0,0,0] op_sel_hi:[0,1,1]
	v_pk_fma_f32 v[44:45], v[34:35], v[126:127], v[44:45] op_sel:[0,0,0] op_sel_hi:[0,1,1]
	v_pk_fma_f32 v[46:47], v[34:35], v[88:89], v[46:47] op_sel:[0,0,0] op_sel_hi:[0,1,1]
	v_pk_fma_f32 v[100:101], v[34:35], v[90:91], v[100:101] op_sel:[0,0,0] op_sel_hi:[0,1,1]
	ds_read2_b32 v[124:125], v33 offset0:47 offset1:48
	ds_read_b32 v126, v33 offset:276
	ds_read2_b32 v[88:89], v33 offset0:70 offset1:71
	ds_read2_b32 v[90:91], v33 offset0:72 offset1:73
	s_waitcnt lgkmcnt(6)
	v_pk_fma_f32 v[36:37], v[34:35], v[92:93], v[36:37] op_sel:[1,0,0] op_sel_hi:[1,1,1]
	v_pk_fma_f32 v[38:39], v[34:35], v[94:95], v[38:39] op_sel:[1,0,0] op_sel_hi:[1,1,1]
	v_pk_fma_f32 v[40:41], v[34:35], v[116:117], v[40:41] op_sel:[1,0,0] op_sel_hi:[1,1,1]
	v_pk_fma_f32 v[42:43], v[34:35], v[118:119], v[42:43] op_sel:[1,0,0] op_sel_hi:[1,1,1]
	ds_read2_b32 v[92:93], v33 offset0:74 offset1:75
	ds_read2_b32 v[94:95], v33 offset0:76 offset1:77
	ds_read2_b32 v[116:117], v33 offset0:78 offset1:79
	ds_read2_b32 v[118:119], v33 offset0:80 offset1:81
	s_waitcnt lgkmcnt(6)
	v_pk_fma_f32 v[44:45], v[34:35], v[120:121], v[44:45] op_sel:[1,0,0] op_sel_hi:[1,1,1]
	v_pk_fma_f32 v[46:47], v[34:35], v[122:123], v[46:47] op_sel:[1,0,0] op_sel_hi:[1,1,1]
	v_pk_fma_f32 v[100:101], v[34:35], v[124:125], v[100:101] op_sel:[1,0,0] op_sel_hi:[1,1,1]
	v_fmac_f32_e32 v37, v36, v126
	ds_read2_b32 v[120:121], v33 offset0:103 offset1:104
	ds_read2_b32 v[122:123], v33 offset0:105 offset1:106
	ds_read2_b32 v[124:125], v33 offset0:107 offset1:108
	ds_read2_b32 v[126:127], v33 offset0:109 offset1:110
	s_waitcnt lgkmcnt(6)
	v_pk_fma_f32 v[38:39], v[36:37], v[88:89], v[38:39] op_sel:[0,0,0] op_sel_hi:[0,1,1]
	v_pk_fma_f32 v[40:41], v[36:37], v[90:91], v[40:41] op_sel:[0,0,0] op_sel_hi:[0,1,1]
	v_pk_fma_f32 v[42:43], v[36:37], v[92:93], v[42:43] op_sel:[0,0,0] op_sel_hi:[0,1,1]
	v_pk_fma_f32 v[44:45], v[36:37], v[94:95], v[44:45] op_sel:[0,0,0] op_sel_hi:[0,1,1]
	ds_read2_b32 v[88:89], v33 offset0:111 offset1:112
	ds_read2_b32 v[90:91], v33 offset0:113 offset1:114
	ds_read_b32 v92, v33 offset:548
	ds_read2_b32 v[94:95], v33 offset0:138 offset1:139
	s_waitcnt lgkmcnt(6)
	v_pk_fma_f32 v[46:47], v[36:37], v[116:117], v[46:47] op_sel:[0,0,0] op_sel_hi:[0,1,1]
	v_pk_fma_f32 v[100:101], v[36:37], v[118:119], v[100:101] op_sel:[0,0,0] op_sel_hi:[0,1,1]
	v_pk_fma_f32 v[38:39], v[36:37], v[120:121], v[38:39] op_sel:[1,0,0] op_sel_hi:[1,1,1]
	v_pk_fma_f32 v[40:41], v[36:37], v[122:123], v[40:41] op_sel:[1,0,0] op_sel_hi:[1,1,1]
	ds_read2_b32 v[116:117], v33 offset0:140 offset1:141
	ds_read2_b32 v[118:119], v33 offset0:142 offset1:143
	ds_read2_b32 v[120:121], v33 offset0:144 offset1:145
	ds_read2_b32 v[122:123], v33 offset0:146 offset1:147
	s_waitcnt lgkmcnt(6)
	v_pk_fma_f32 v[42:43], v[36:37], v[124:125], v[42:43] op_sel:[1,0,0] op_sel_hi:[1,1,1]
	v_pk_fma_f32 v[44:45], v[36:37], v[126:127], v[44:45] op_sel:[1,0,0] op_sel_hi:[1,1,1]
	v_pk_fma_f32 v[46:47], v[36:37], v[88:89], v[46:47] op_sel:[1,0,0] op_sel_hi:[1,1,1]
	v_pk_fma_f32 v[100:101], v[36:37], v[90:91], v[100:101] op_sel:[1,0,0] op_sel_hi:[1,1,1]
	ds_read2_b32 v[124:125], v33 offset0:171 offset1:172
	ds_read2_b32 v[126:127], v33 offset0:173 offset1:174
	ds_read2_b32 v[88:89], v33 offset0:175 offset1:176
	ds_read2_b32 v[90:91], v33 offset0:177 offset1:178
	s_waitcnt lgkmcnt(6)
	v_fmac_f32_e32 v39, v38, v92
	v_pk_fma_f32 v[40:41], v[38:39], v[94:95], v[40:41] op_sel:[0,0,0] op_sel_hi:[0,1,1]
	v_pk_fma_f32 v[42:43], v[38:39], v[116:117], v[42:43] op_sel:[0,0,0] op_sel_hi:[0,1,1]
	v_pk_fma_f32 v[44:45], v[38:39], v[118:119], v[44:45] op_sel:[0,0,0] op_sel_hi:[0,1,1]
	ds_read2_b32 v[92:93], v33 offset0:179 offset1:180
	ds_read_b32 v94, v33 offset:820
	ds_read2_b32 v[116:117], v33 offset0:206 offset1:207
	ds_read2_b32 v[118:119], v33 offset0:208 offset1:209
	s_waitcnt lgkmcnt(6)
	v_pk_fma_f32 v[46:47], v[38:39], v[120:121], v[46:47] op_sel:[0,0,0] op_sel_hi:[0,1,1]
	v_pk_fma_f32 v[100:101], v[38:39], v[122:123], v[100:101] op_sel:[0,0,0] op_sel_hi:[0,1,1]
	v_pk_fma_f32 v[40:41], v[38:39], v[124:125], v[40:41] op_sel:[1,0,0] op_sel_hi:[1,1,1]
	v_pk_fma_f32 v[42:43], v[38:39], v[126:127], v[42:43] op_sel:[1,0,0] op_sel_hi:[1,1,1]
	ds_read2_b32 v[120:121], v33 offset0:210 offset1:211
	ds_read2_b32 v[122:123], v33 offset0:212 offset1:213
	ds_read2_b32 v[124:125], v33 offset0:239 offset1:240
	ds_read2_b32 v[126:127], v33 offset0:241 offset1:242
	s_waitcnt lgkmcnt(6)
	v_pk_fma_f32 v[44:45], v[38:39], v[88:89], v[44:45] op_sel:[1,0,0] op_sel_hi:[1,1,1]
	v_pk_fma_f32 v[46:47], v[38:39], v[90:91], v[46:47] op_sel:[1,0,0] op_sel_hi:[1,1,1]
	v_pk_fma_f32 v[100:101], v[38:39], v[92:93], v[100:101] op_sel:[1,0,0] op_sel_hi:[1,1,1]
	v_fmac_f32_e32 v41, v40, v94
	ds_read2_b32 v[88:89], v33 offset0:243 offset1:244
	ds_read2_b32 v[90:91], v33 offset0:245 offset1:246
	ds_read_b32 v92, v96 offset:36
	ds_read2_b32 v[94:95], v96 offset0:10 offset1:11
	s_waitcnt lgkmcnt(6)
	v_pk_fma_f32 v[42:43], v[40:41], v[116:117], v[42:43] op_sel:[0,0,0] op_sel_hi:[0,1,1]
	v_pk_fma_f32 v[44:45], v[40:41], v[118:119], v[44:45] op_sel:[0,0,0] op_sel_hi:[0,1,1]
	v_pk_fma_f32 v[46:47], v[40:41], v[120:121], v[46:47] op_sel:[0,0,0] op_sel_hi:[0,1,1]
	v_pk_fma_f32 v[100:101], v[40:41], v[122:123], v[100:101] op_sel:[0,0,0] op_sel_hi:[0,1,1]
	ds_read2_b32 v[116:117], v96 offset0:12 offset1:13
	ds_read2_b32 v[118:119], v96 offset0:14 offset1:15
	ds_read2_b32 v[120:121], v96 offset0:43 offset1:44
	ds_read2_b32 v[122:123], v96 offset0:45 offset1:46
	s_waitcnt lgkmcnt(6)
	v_pk_fma_f32 v[42:43], v[40:41], v[124:125], v[42:43] op_sel:[1,0,0] op_sel_hi:[1,1,1]
	v_pk_fma_f32 v[44:45], v[40:41], v[126:127], v[44:45] op_sel:[1,0,0] op_sel_hi:[1,1,1]
	v_pk_fma_f32 v[46:47], v[40:41], v[88:89], v[46:47] op_sel:[1,0,0] op_sel_hi:[1,1,1]
	v_pk_fma_f32 v[100:101], v[40:41], v[90:91], v[100:101] op_sel:[1,0,0] op_sel_hi:[1,1,1]
	ds_read2_b32 v[124:125], v96 offset0:47 offset1:48
	ds_read_b32 v126, v96 offset:308
	ds_read2_b32 v[88:89], v96 offset0:78 offset1:79
	ds_read2_b32 v[90:91], v96 offset0:80 offset1:81
	s_waitcnt lgkmcnt(6)
	v_fmac_f32_e32 v43, v42, v92
	v_pk_fma_f32 v[44:45], v[42:43], v[94:95], v[44:45] op_sel:[0,0,0] op_sel_hi:[0,1,1]
	v_pk_fma_f32 v[46:47], v[42:43], v[116:117], v[46:47] op_sel:[0,0,0] op_sel_hi:[0,1,1]
	v_pk_fma_f32 v[100:101], v[42:43], v[118:119], v[100:101] op_sel:[0,0,0] op_sel_hi:[0,1,1]
	ds_read2_b32 v[92:93], v96 offset0:111 offset1:112
	ds_read2_b32 v[94:95], v96 offset0:113 offset1:114
	ds_read_b32 v116, v96 offset:580
	ds_read2_b32 v[118:119], v96 offset0:146 offset1:147
	s_waitcnt lgkmcnt(6)
	v_pk_fma_f32 v[44:45], v[42:43], v[120:121], v[44:45] op_sel:[1,0,0] op_sel_hi:[1,1,1]
	v_pk_fma_f32 v[46:47], v[42:43], v[122:123], v[46:47] op_sel:[1,0,0] op_sel_hi:[1,1,1]
	v_pk_fma_f32 v[100:101], v[42:43], v[124:125], v[100:101] op_sel:[1,0,0] op_sel_hi:[1,1,1]
	v_fmac_f32_e32 v45, v44, v126
	ds_read2_b32 v[120:121], v96 offset0:179 offset1:180
	ds_read_b32 v122, v96 offset:852
	s_waitcnt lgkmcnt(4)
	v_pk_fma_f32 v[46:47], v[44:45], v[88:89], v[46:47] op_sel:[0,0,0] op_sel_hi:[0,1,1]
	v_pk_fma_f32 v[100:101], v[44:45], v[90:91], v[100:101] op_sel:[0,0,0] op_sel_hi:[0,1,1]
	v_pk_fma_f32 v[46:47], v[44:45], v[92:93], v[46:47] op_sel:[1,0,0] op_sel_hi:[1,1,1]
	v_pk_fma_f32 v[100:101], v[44:45], v[94:95], v[100:101] op_sel:[1,0,0] op_sel_hi:[1,1,1]
	s_waitcnt lgkmcnt(0)
	v_fmac_f32_e32 v47, v46, v116
	v_pk_fma_f32 v[100:101], v[46:47], v[118:119], v[100:101] op_sel:[0,0,0] op_sel_hi:[0,1,1]
	v_pk_fma_f32 v[100:101], v[46:47], v[120:121], v[100:101] op_sel:[1,0,0] op_sel_hi:[1,1,1]
	v_fmac_f32_e32 v101, v100, v122
	v_mul_u32_u24_e32 v33, 0x440, v99
	v_mul_u32_u24_e32 v96, 0x520, v99
	v_mul_u32_u24_e32 v99, 0x44, v32
	v_add_u32_e32 v33, v33, v99
	v_lshl_add_u32 v96, v32, 1, v96
	v_add_u32_e32 v33, 0x3100, v33
	v_add_u32_e32 v96, 0xe3c0, v96
	ds_write2_b32 v33, v34, v35 offset0:0 offset1:1
	ds_write2_b32 v33, v36, v37 offset0:2 offset1:3
	ds_write2_b32 v33, v38, v39 offset0:4 offset1:5
	ds_write2_b32 v33, v40, v41 offset0:6 offset1:7
	ds_write2_b32 v33, v42, v43 offset0:8 offset1:9
	ds_write2_b32 v33, v44, v45 offset0:10 offset1:11
	ds_write2_b32 v33, v46, v47 offset0:12 offset1:13
	ds_write2_b32 v33, v100, v101 offset0:14 offset1:15
	v_cvt_pk_bf16_f32 v116, v34, v35
	ds_write_b16 v96, v116 offset:0
	ds_write_b16_d16_hi v96, v116 offset:80
	v_cvt_pk_bf16_f32 v118, v36, v37
	ds_write_b16 v96, v118 offset:160
	ds_write_b16_d16_hi v96, v118 offset:240
	v_cvt_pk_bf16_f32 v120, v38, v39
	ds_write_b16 v96, v120 offset:320
	ds_write_b16_d16_hi v96, v120 offset:400
	v_cvt_pk_bf16_f32 v122, v40, v41
	ds_write_b16 v96, v122 offset:480
	ds_write_b16_d16_hi v96, v122 offset:560
	v_cvt_pk_bf16_f32 v124, v42, v43
	ds_write_b16 v96, v124 offset:640
	ds_write_b16_d16_hi v96, v124 offset:720
	v_cvt_pk_bf16_f32 v126, v44, v45
	ds_write_b16 v96, v126 offset:800
	ds_write_b16_d16_hi v96, v126 offset:880
	v_cvt_pk_bf16_f32 v88, v46, v47
	ds_write_b16 v96, v88 offset:960
	ds_write_b16_d16_hi v96, v88 offset:1040
	v_cvt_pk_bf16_f32 v90, v100, v101
	ds_write_b16 v96, v90 offset:1120
	ds_write_b16_d16_hi v96, v90 offset:1200

.LBB0_1149:
	v_mul_u32_u24_e32 v34, 0x48, v70
	v_lshlrev_b32_e32 v66, 1, v34
	s_waitcnt lgkmcnt(0)
	s_barrier
	v_add3_u32 v50, s89, v66, v0
	ds_read_b128 v[34:37], v50
	v_add3_u32 v0, s90, v66, v0
	ds_read_b128 v[38:41], v0
	ds_read_b128 v[52:55], v50 offset:32
	ds_read_b128 v[56:59], v0 offset:32
	s_mov_b64 s[58:59], -1
	s_and_b64 vcc, exec, s[54:55]
	s_waitcnt lgkmcnt(2)
	v_mfma_f32_32x32x16_bf16 v[34:49], v[34:37], v[38:41], 0
	s_waitcnt lgkmcnt(0)
	v_mfma_f32_32x32x16_bf16 v[34:49], v[52:55], v[56:59], v[34:49]
	ds_read_b128 v[52:55], v50 offset:64
	ds_read_b128 v[56:59], v0 offset:64
	ds_read_b128 v[60:63], v50 offset:96
	ds_read_b128 v[72:75], v0 offset:96
	v_lshlrev_b32_e32 v0, 2, v51
	v_cmp_lt_u32_e64 s[12:13], v70, v0
	v_lshl_add_u32 v50, v70, 1, s91
	s_waitcnt lgkmcnt(2)
	v_mfma_f32_32x32x16_bf16 v[34:49], v[52:55], v[56:59], v[34:49]
	v_cndmask_b32_e64 v52, 0, 1, s[12:13]
	v_cmp_le_u32_e64 s[12:13], v70, v0
	s_nop 1
	v_cndmask_b32_e64 v53, 0, 1, s[12:13]
	v_cndmask_b32_e64 v52, v53, v52, s[8:9]
	v_and_b32_e32 v52, 1, v52
	s_waitcnt lgkmcnt(0)
	v_mfma_f32_32x32x16_bf16 v[34:49], v[60:63], v[72:75], v[34:49]
	v_or_b32_e32 v143, 1, v0
	v_or_b32_e32 v158, 2, v0
	v_or_b32_e32 v159, 3, v0
	v_or_b32_e32 v160, 8, v0
	v_or_b32_e32 v161, 9, v0
	v_or_b32_e32 v162, 10, v0
	v_or_b32_e32 v163, 11, v0
	v_or_b32_e32 v164, 16, v0
	v_or_b32_e32 v165, 17, v0
	v_or_b32_e32 v166, 18, v0
	v_or_b32_e32 v167, 19, v0
	v_or_b32_e32 v168, 24, v0
	v_or_b32_e32 v169, 25, v0
	v_or_b32_e32 v170, 26, v0
	v_or_b32_e32 v171, 27, v0
	s_cmp_eq_u64 s[54:55], 0
	s_cbranch_scc1 .Ld_w0_b
	s_cmp_eq_u64 s[8:9], 0
	s_cbranch_scc1 .Ld_w23_b
	v_mul_u32_u24_e32 v52, 0x50, v0
	v_add_u32_e32 v52, v52, v50
	v_cmp_lt_u32_e32 vcc, v70, v0
	v_cmp_lt_u32_e64 s[12:13], v70, v143
	v_cmp_lt_u32_e64 s[58:59], v70, v158
	v_cndmask_b32_e64 v34, 0, v34, vcc
	v_cmp_lt_u32_e32 vcc, v70, v159
	v_cndmask_b32_e64 v35, 0, v35, s[12:13]
	v_cmp_lt_u32_e64 s[12:13], v70, v160
	v_cvt_pk_bf16_f32 v53, v34, v35
	ds_write_b16 v52, v53 offset:0
	ds_write_b16_d16_hi v52, v53 offset:80
	v_cndmask_b32_e64 v36, 0, v36, s[58:59]
	v_cmp_lt_u32_e64 s[58:59], v70, v161
	v_cndmask_b32_e64 v37, 0, v37, vcc
	v_cmp_lt_u32_e32 vcc, v70, v162
	v_cvt_pk_bf16_f32 v53, v36, v37
	ds_write_b16 v52, v53 offset:160
	ds_write_b16_d16_hi v52, v53 offset:240
	v_cndmask_b32_e64 v38, 0, v38, s[12:13]
	v_cmp_lt_u32_e64 s[12:13], v70, v163
	v_cndmask_b32_e64 v39, 0, v39, s[58:59]
	v_cmp_lt_u32_e64 s[58:59], v70, v164
	v_cvt_pk_bf16_f32 v53, v38, v39
	ds_write_b16 v52, v53 offset:640
	ds_write_b16_d16_hi v52, v53 offset:720
	v_cndmask_b32_e64 v40, 0, v40, vcc
	v_cmp_lt_u32_e32 vcc, v70, v165
	v_cndmask_b32_e64 v41, 0, v41, s[12:13]
	v_cmp_lt_u32_e64 s[12:13], v70, v166
	v_cvt_pk_bf16_f32 v53, v40, v41
	ds_write_b16 v52, v53 offset:800
	ds_write_b16_d16_hi v52, v53 offset:880
	v_cndmask_b32_e64 v42, 0, v42, s[58:59]
	v_cmp_lt_u32_e64 s[58:59], v70, v167
	v_cndmask_b32_e64 v43, 0, v43, vcc
	v_cmp_lt_u32_e32 vcc, v70, v168
	v_cvt_pk_bf16_f32 v53, v42, v43
	ds_write_b16 v52, v53 offset:1280
	ds_write_b16_d16_hi v52, v53 offset:1360
	v_cndmask_b32_e64 v44, 0, v44, s[12:13]
	v_cmp_lt_u32_e64 s[12:13], v70, v169
	v_cndmask_b32_e64 v45, 0, v45, s[58:59]
	v_cmp_lt_u32_e64 s[58:59], v70, v170
	v_cvt_pk_bf16_f32 v53, v44, v45
	ds_write_b16 v52, v53 offset:1440
	ds_write_b16_d16_hi v52, v53 offset:1520
	v_cndmask_b32_e64 v46, 0, v46, vcc
	v_cmp_lt_u32_e32 vcc, v70, v171
	v_cndmask_b32_e64 v47, 0, v47, s[12:13]
	v_cvt_pk_bf16_f32 v53, v46, v47
	ds_write_b16 v52, v53 offset:1920
	ds_write_b16_d16_hi v52, v53 offset:2000
	v_cndmask_b32_e64 v48, 0, v48, s[58:59]
	v_cndmask_b32_e64 v49, 0, v49, vcc
	v_cvt_pk_bf16_f32 v53, v48, v49
	ds_write_b16 v52, v53 offset:2080
	ds_write_b16_d16_hi v52, v53 offset:2160
	s_branch .Ld_done_b
.Ld_w23_b:
	v_mul_u32_u24_e32 v52, 0x50, v0
	v_add_u32_e32 v52, v52, v50
	v_cmp_le_u32_e32 vcc, v70, v0
	v_cmp_le_u32_e64 s[12:13], v70, v143
	v_cmp_le_u32_e64 s[58:59], v70, v158
	v_cndmask_b32_e64 v34, 0, v34, vcc
	v_cmp_le_u32_e32 vcc, v70, v159
	v_cndmask_b32_e64 v35, 0, v35, s[12:13]
	v_cmp_le_u32_e64 s[12:13], v70, v160
	v_cvt_pk_bf16_f32 v53, v34, v35
	ds_write_b16 v52, v53 offset:0
	ds_write_b16_d16_hi v52, v53 offset:80
	v_cndmask_b32_e64 v36, 0, v36, s[58:59]
	v_cmp_le_u32_e64 s[58:59], v70, v161
	v_cndmask_b32_e64 v37, 0, v37, vcc
	v_cmp_le_u32_e32 vcc, v70, v162
	v_cvt_pk_bf16_f32 v53, v36, v37
	ds_write_b16 v52, v53 offset:160
	ds_write_b16_d16_hi v52, v53 offset:240
	v_cndmask_b32_e64 v38, 0, v38, s[12:13]
	v_cmp_le_u32_e64 s[12:13], v70, v163
	v_cndmask_b32_e64 v39, 0, v39, s[58:59]
	v_cmp_le_u32_e64 s[58:59], v70, v164
	v_cvt_pk_bf16_f32 v53, v38, v39
	ds_write_b16 v52, v53 offset:640
	ds_write_b16_d16_hi v52, v53 offset:720
	v_cndmask_b32_e64 v40, 0, v40, vcc
	v_cmp_le_u32_e32 vcc, v70, v165
	v_cndmask_b32_e64 v41, 0, v41, s[12:13]
	v_cmp_le_u32_e64 s[12:13], v70, v166
	v_cvt_pk_bf16_f32 v53, v40, v41
	ds_write_b16 v52, v53 offset:800
	ds_write_b16_d16_hi v52, v53 offset:880
	v_cndmask_b32_e64 v42, 0, v42, s[58:59]
	v_cmp_le_u32_e64 s[58:59], v70, v167
	v_cndmask_b32_e64 v43, 0, v43, vcc
	v_cmp_le_u32_e32 vcc, v70, v168
	v_cvt_pk_bf16_f32 v53, v42, v43
	ds_write_b16 v52, v53 offset:1280
	ds_write_b16_d16_hi v52, v53 offset:1360
	v_cndmask_b32_e64 v44, 0, v44, s[12:13]
	v_cmp_le_u32_e64 s[12:13], v70, v169
	v_cndmask_b32_e64 v45, 0, v45, s[58:59]
	v_cmp_le_u32_e64 s[58:59], v70, v170
	v_cvt_pk_bf16_f32 v53, v44, v45
	ds_write_b16 v52, v53 offset:1440
	ds_write_b16_d16_hi v52, v53 offset:1520
	v_cndmask_b32_e64 v46, 0, v46, vcc
	v_cmp_le_u32_e32 vcc, v70, v171
	v_cndmask_b32_e64 v47, 0, v47, s[12:13]
	v_cvt_pk_bf16_f32 v53, v46, v47
	ds_write_b16 v52, v53 offset:1920
	ds_write_b16_d16_hi v52, v53 offset:2000
	v_cndmask_b32_e64 v48, 0, v48, s[58:59]
	v_cndmask_b32_e64 v49, 0, v49, vcc
	v_cvt_pk_bf16_f32 v53, v48, v49
	ds_write_b16 v52, v53 offset:2080
	ds_write_b16_d16_hi v52, v53 offset:2160
	s_branch .Ld_done_b
.Ld_w0_b:
	v_mul_u32_u24_e32 v52, 0x84, v70
	v_lshl_add_u32 v52, v0, 2, v52
	v_add_u32_e32 v52, 0x2080, v52
	v_cmp_lt_u32_e32 vcc, v70, v0
	v_cmp_lt_u32_e64 s[12:13], v70, v143
	v_cmp_lt_u32_e64 s[58:59], v70, v158
	v_cndmask_b32_e64 v34, 0, v34, vcc
	v_cmp_lt_u32_e32 vcc, v70, v159
	v_cndmask_b32_e64 v35, 0, v35, s[12:13]
	v_cmp_lt_u32_e64 s[12:13], v70, v160
	ds_write2_b32 v52, v34, v35 offset0:0 offset1:1
	v_cndmask_b32_e64 v36, 0, v36, s[58:59]
	v_cmp_lt_u32_e64 s[58:59], v70, v161
	v_cndmask_b32_e64 v37, 0, v37, vcc
	v_cmp_lt_u32_e32 vcc, v70, v162
	ds_write2_b32 v52, v36, v37 offset0:2 offset1:3
	v_cndmask_b32_e64 v38, 0, v38, s[12:13]
	v_cmp_lt_u32_e64 s[12:13], v70, v163
	v_cndmask_b32_e64 v39, 0, v39, s[58:59]
	v_cmp_lt_u32_e64 s[58:59], v70, v164
	ds_write2_b32 v52, v38, v39 offset0:8 offset1:9
	v_cndmask_b32_e64 v40, 0, v40, vcc
	v_cmp_lt_u32_e32 vcc, v70, v165
	v_cndmask_b32_e64 v41, 0, v41, s[12:13]
	v_cmp_lt_u32_e64 s[12:13], v70, v166
	ds_write2_b32 v52, v40, v41 offset0:10 offset1:11
	v_cndmask_b32_e64 v42, 0, v42, s[58:59]
	v_cmp_lt_u32_e64 s[58:59], v70, v167
	v_cndmask_b32_e64 v43, 0, v43, vcc
	v_cmp_lt_u32_e32 vcc, v70, v168
	ds_write2_b32 v52, v42, v43 offset0:16 offset1:17
	v_cndmask_b32_e64 v44, 0, v44, s[12:13]
	v_cmp_lt_u32_e64 s[12:13], v70, v169
	v_cndmask_b32_e64 v45, 0, v45, s[58:59]
	v_cmp_lt_u32_e64 s[58:59], v70, v170
	ds_write2_b32 v52, v44, v45 offset0:18 offset1:19
	v_cndmask_b32_e64 v46, 0, v46, vcc
	v_cmp_lt_u32_e32 vcc, v70, v171
	v_cndmask_b32_e64 v47, 0, v47, s[12:13]
	ds_write2_b32 v52, v46, v47 offset0:24 offset1:25
	v_cndmask_b32_e64 v48, 0, v48, s[58:59]
	v_cndmask_b32_e64 v49, 0, v49, vcc
	ds_write2_b32 v52, v48, v49 offset0:26 offset1:27
.Ld_done_b:
.LBB0_1211:
	v_cmp_gt_i32_e32 vcc, 32, v141
	v_and_b32_e32 v34, 15, v141
	s_and_saveexec_b64 s[58:59], vcc
	s_cbranch_execz .LBB0_1213

.LBB0_1278:
	v_mul_u32_u24_e32 v34, 0x48, v70
	v_lshlrev_b32_e32 v66, 1, v34
	s_waitcnt lgkmcnt(0)
	s_barrier
	v_add3_u32 v50, s85, v66, v0
	ds_read_b128 v[34:37], v50
	v_add3_u32 v0, s86, v66, v0
	ds_read_b128 v[38:41], v0
	ds_read_b128 v[52:55], v50 offset:32
	ds_read_b128 v[56:59], v0 offset:32
	s_mov_b64 s[58:59], -1
	s_and_b64 vcc, exec, s[54:55]
	s_waitcnt lgkmcnt(2)
	v_mfma_f32_32x32x16_bf16 v[34:49], v[34:37], v[38:41], 0
	s_waitcnt lgkmcnt(0)
	v_mfma_f32_32x32x16_bf16 v[34:49], v[52:55], v[56:59], v[34:49]
	ds_read_b128 v[52:55], v50 offset:64
	ds_read_b128 v[56:59], v0 offset:64
	ds_read_b128 v[60:63], v50 offset:96
	ds_read_b128 v[72:75], v0 offset:96
	v_lshlrev_b32_e32 v0, 2, v51
	v_cmp_lt_u32_e64 s[12:13], v70, v0
	v_lshl_add_u32 v50, v70, 1, s87
	s_waitcnt lgkmcnt(2)
	v_mfma_f32_32x32x16_bf16 v[34:49], v[52:55], v[56:59], v[34:49]
	v_cndmask_b32_e64 v52, 0, 1, s[12:13]
	v_cmp_le_u32_e64 s[12:13], v70, v0
	s_nop 1
	v_cndmask_b32_e64 v53, 0, 1, s[12:13]
	v_cndmask_b32_e64 v52, v53, v52, s[8:9]
	v_and_b32_e32 v52, 1, v52
	s_waitcnt lgkmcnt(0)
	v_mfma_f32_32x32x16_bf16 v[34:49], v[60:63], v[72:75], v[34:49]
	v_or_b32_e32 v143, 1, v0
	v_or_b32_e32 v158, 2, v0
	v_or_b32_e32 v159, 3, v0
	v_or_b32_e32 v160, 8, v0
	v_or_b32_e32 v161, 9, v0
	v_or_b32_e32 v162, 10, v0
	v_or_b32_e32 v163, 11, v0
	v_or_b32_e32 v164, 16, v0
	v_or_b32_e32 v165, 17, v0
	v_or_b32_e32 v166, 18, v0
	v_or_b32_e32 v167, 19, v0
	v_or_b32_e32 v168, 24, v0
	v_or_b32_e32 v169, 25, v0
	v_or_b32_e32 v170, 26, v0
	v_or_b32_e32 v171, 27, v0
	s_cmp_eq_u64 s[54:55], 0
	s_cbranch_scc1 .Ld_w0_c
	s_cmp_eq_u64 s[8:9], 0
	s_cbranch_scc1 .Ld_w23_c
	v_mul_u32_u24_e32 v52, 0x50, v0
	v_add_u32_e32 v52, v52, v50
	v_cmp_lt_u32_e32 vcc, v70, v0
	v_cmp_lt_u32_e64 s[12:13], v70, v143
	v_cmp_lt_u32_e64 s[58:59], v70, v158
	v_cndmask_b32_e64 v34, 0, v34, vcc
	v_cmp_lt_u32_e32 vcc, v70, v159
	v_cndmask_b32_e64 v35, 0, v35, s[12:13]
	v_cmp_lt_u32_e64 s[12:13], v70, v160
	v_cvt_pk_bf16_f32 v53, v34, v35
	ds_write_b16 v52, v53 offset:0
	ds_write_b16_d16_hi v52, v53 offset:80
	v_cndmask_b32_e64 v36, 0, v36, s[58:59]
	v_cmp_lt_u32_e64 s[58:59], v70, v161
	v_cndmask_b32_e64 v37, 0, v37, vcc
	v_cmp_lt_u32_e32 vcc, v70, v162
	v_cvt_pk_bf16_f32 v53, v36, v37
	ds_write_b16 v52, v53 offset:160
	ds_write_b16_d16_hi v52, v53 offset:240
	v_cndmask_b32_e64 v38, 0, v38, s[12:13]
	v_cmp_lt_u32_e64 s[12:13], v70, v163
	v_cndmask_b32_e64 v39, 0, v39, s[58:59]
	v_cmp_lt_u32_e64 s[58:59], v70, v164
	v_cvt_pk_bf16_f32 v53, v38, v39
	ds_write_b16 v52, v53 offset:640
	ds_write_b16_d16_hi v52, v53 offset:720
	v_cndmask_b32_e64 v40, 0, v40, vcc
	v_cmp_lt_u32_e32 vcc, v70, v165
	v_cndmask_b32_e64 v41, 0, v41, s[12:13]
	v_cmp_lt_u32_e64 s[12:13], v70, v166
	v_cvt_pk_bf16_f32 v53, v40, v41
	ds_write_b16 v52, v53 offset:800
	ds_write_b16_d16_hi v52, v53 offset:880
	v_cndmask_b32_e64 v42, 0, v42, s[58:59]
	v_cmp_lt_u32_e64 s[58:59], v70, v167
	v_cndmask_b32_e64 v43, 0, v43, vcc
	v_cmp_lt_u32_e32 vcc, v70, v168
	v_cvt_pk_bf16_f32 v53, v42, v43
	ds_write_b16 v52, v53 offset:1280
	ds_write_b16_d16_hi v52, v53 offset:1360
	v_cndmask_b32_e64 v44, 0, v44, s[12:13]
	v_cmp_lt_u32_e64 s[12:13], v70, v169
	v_cndmask_b32_e64 v45, 0, v45, s[58:59]
	v_cmp_lt_u32_e64 s[58:59], v70, v170
	v_cvt_pk_bf16_f32 v53, v44, v45
	ds_write_b16 v52, v53 offset:1440
	ds_write_b16_d16_hi v52, v53 offset:1520
	v_cndmask_b32_e64 v46, 0, v46, vcc
	v_cmp_lt_u32_e32 vcc, v70, v171
	v_cndmask_b32_e64 v47, 0, v47, s[12:13]
	v_cvt_pk_bf16_f32 v53, v46, v47
	ds_write_b16 v52, v53 offset:1920
	ds_write_b16_d16_hi v52, v53 offset:2000
	v_cndmask_b32_e64 v48, 0, v48, s[58:59]
	v_cndmask_b32_e64 v49, 0, v49, vcc
	v_cvt_pk_bf16_f32 v53, v48, v49
	ds_write_b16 v52, v53 offset:2080
	ds_write_b16_d16_hi v52, v53 offset:2160
	s_branch .Ld_done_c
